# streaming (nt) policy for read-once P4 gate loads, P5 residual loads and P5 out stores, on top of v11
# baseline (speedup 1.0000x reference)
;     __device__ __forceinline__ void operator()(const f32x4 (&acc)[2][2][4][2], const UnitD& u, int wr, int wc, int lane, LAS unsigned char* eb) const {
;     ...
;         const bf16_t* G = G0 + (u.tag & 3) * DM; const bool first = (u.tag & 4) != 0;
; #pragma unroll
;         for (int ai = 0; ai < 2; ++ai) {
;             u32x4 gw[4][2], ow[4][2];
; #pragma unroll
;             for (int m = 0; m < 4; ++m)
; #pragma unroll
;                 for (int hf = 0; hf < 2; ++hf) { const int r = 8 * hf + rr, c = cl ^ (r & 7); const size_t row = (size_t)(u.pm * BM + ai * HALF + wr * 64 + m * 16 + r);
;                     gw[m][hf] = *(const u32x4*)(G + row * ldg + colw + 8 * c);
;                     ow[m][hf] = first ? (u32x4){0u, 0u, 0u, 0u} : *(const u32x4*)(O + row * DM + colw + 8 * c); }
.LBB0_499:
	s_lshl_b32 s4, s55, 8
	s_lshl_b32 s5, s54, 12
	s_or_b32 s4, s4, s46
	s_and_b32 s5, s5, 0x3000
	s_add_u32 s26, s40, s5
	s_addc_u32 s27, s41, 0
	s_and_b32 s33, s54, 4
	v_mov_b32_e32 v121, v234
	s_cmp_eq_u32 s33, 0
	s_cselect_b64 s[24:25], -1, 0
	v_ashrrev_i32_e32 v237, 3, v121
	s_ashr_i32 s5, s4, 31
	s_lshl_b64 s[22:23], s[4:5], 1
	v_xor_b32_e32 v120, v237, v121
	s_add_u32 s4, s26, s22
	v_lshlrev_b32_e32 v120, 3, v120
	s_addc_u32 s5, s27, s23
	s_lshl_b32 s26, s53, 8
	v_and_b32_e32 v120, 56, v120
	s_add_i32 s26, s26, s42
	v_lshlrev_b32_e32 v194, 1, v120
	v_lshl_add_u64 v[214:215], s[4:5], 0, v[194:195]
	v_add_u32_e32 v216, s26, v237
	v_mad_i64_i32 v[130:131], s[4:5], v216, s65, v[214:215]
	global_load_dwordx4 v[186:189], v[130:131], off nt
	s_add_u32 s4, s10, s22
	s_addc_u32 s5, s11, s23
	v_ashrrev_i32_e32 v217, 31, v216
	v_mov_b32_e32 v240, 0xfff79000
	s_cmp_lg_u32 s33, 0
	v_lshl_add_u64 v[212:213], s[4:5], 0, v[194:195]
	v_mov_b32_e32 v162, 0
	v_lshlrev_b64 v[232:233], 12, v[216:217]
	v_mov_b32_e32 v190, 0
	v_mov_b32_e32 v191, 0
	v_mov_b32_e32 v192, 0
	v_mov_b32_e32 v193, 0
	s_cbranch_scc1 .LBB0_501
	v_lshl_add_u64 v[130:131], v[212:213], 0, v[232:233]
	global_load_dwordx4 v[190:193], v[130:131], off
.LBB0_501:
	v_add_u32_e32 v130, 8, v216
	v_mad_i64_i32 v[132:133], s[4:5], v130, s65, v[214:215]
	global_load_dwordx4 v[178:181], v[132:133], off nt
	v_ashrrev_i32_e32 v131, 31, v130
	v_cndmask_b32_e64 v120, 0, 1, s[24:25]
	v_mov_b32_e32 v241, 0xfff82000
	v_mov_b32_e32 v249, 0xfffe5000
	v_cmp_ne_u32_e64 s[4:5], 1, v120
	s_andn2_b64 vcc, exec, s[24:25]
	v_lshlrev_b64 v[230:231], 12, v[130:131]
	v_mov_b32_e32 v182, 0
	v_mov_b32_e32 v183, 0
	v_mov_b32_e32 v184, 0
	v_mov_b32_e32 v185, 0
	s_cbranch_vccnz .LBB0_503
	v_lshl_add_u64 v[130:131], v[212:213], 0, v[230:231]
	global_load_dwordx4 v[182:185], v[130:131], off
.LBB0_503:
	v_add_u32_e32 v130, 16, v216
	v_mad_i64_i32 v[132:133], s[24:25], v130, s65, v[214:215]
	global_load_dwordx4 v[174:177], v[132:133], off nt
	v_ashrrev_i32_e32 v131, 31, v130
	v_mov_b32_e32 v242, 0xfff8b000
	v_mov_b32_e32 v248, 0xfffee000
	s_and_b64 vcc, exec, s[4:5]
	v_lshlrev_b64 v[228:229], 12, v[130:131]
	v_mov_b32_e32 v163, 0
	v_mov_b32_e32 v164, 0
	v_mov_b32_e32 v165, 0
	s_cbranch_vccnz .LBB0_505
	v_lshl_add_u64 v[130:131], v[212:213], 0, v[228:229]
	global_load_dwordx4 v[162:165], v[130:131], off
.LBB0_505:
	v_add_u32_e32 v130, 24, v216
	v_mad_i64_i32 v[132:133], s[24:25], v130, s65, v[214:215]
	global_load_dwordx4 v[166:169], v[132:133], off nt
	v_ashrrev_i32_e32 v131, 31, v130
	v_mov_b32_e32 v247, 0xffff7000
	v_mov_b32_e32 v150, 0
	s_and_b64 vcc, exec, s[4:5]
	v_lshlrev_b64 v[226:227], 12, v[130:131]
	v_mov_b32_e32 v170, 0
	v_mov_b32_e32 v171, 0
	v_mov_b32_e32 v172, 0
	v_mov_b32_e32 v173, 0
	s_cbranch_vccnz .LBB0_507
	v_lshl_add_u64 v[130:131], v[212:213], 0, v[226:227]
	global_load_dwordx4 v[170:173], v[130:131], off
.LBB0_507:
	v_add_u32_e32 v130, 32, v216
	v_mad_i64_i32 v[132:133], s[24:25], v130, s65, v[214:215]
	global_load_dwordx4 v[158:161], v[132:133], off nt
	v_ashrrev_i32_e32 v131, 31, v130
	s_and_b64 vcc, exec, s[4:5]
	v_lshlrev_b64 v[224:225], 12, v[130:131]
	v_mov_b32_e32 v151, 0
	v_mov_b32_e32 v152, 0
	v_mov_b32_e32 v153, 0
	s_cbranch_vccnz .LBB0_509
	v_lshl_add_u64 v[130:131], v[212:213], 0, v[224:225]
	global_load_dwordx4 v[150:153], v[130:131], off
.LBB0_509:
	v_add_u32_e32 v130, 40, v216
	v_mad_i64_i32 v[132:133], s[24:25], v130, s65, v[214:215]
	global_load_dwordx4 v[146:149], v[132:133], off nt
	v_ashrrev_i32_e32 v131, 31, v130
	v_mov_b32_e32 v134, 0
	s_and_b64 vcc, exec, s[4:5]
	v_lshlrev_b64 v[222:223], 12, v[130:131]
	v_mov_b32_e32 v154, 0
	v_mov_b32_e32 v155, 0
	v_mov_b32_e32 v156, 0
	v_mov_b32_e32 v157, 0
	s_cbranch_vccnz .LBB0_511
	v_lshl_add_u64 v[130:131], v[212:213], 0, v[222:223]
	global_load_dwordx4 v[154:157], v[130:131], off
.LBB0_511:
	v_add_u32_e32 v130, 48, v216
	v_mad_i64_i32 v[132:133], s[24:25], v130, s65, v[214:215]
	global_load_dwordx4 v[142:145], v[132:133], off nt
	v_ashrrev_i32_e32 v131, 31, v130
	s_and_b64 vcc, exec, s[4:5]
	v_lshlrev_b64 v[220:221], 12, v[130:131]
	v_mov_b32_e32 v135, 0
	v_mov_b32_e32 v136, 0
	v_mov_b32_e32 v137, 0
	s_cbranch_vccnz .LBB0_513
	v_lshl_add_u64 v[130:131], v[212:213], 0, v[220:221]
	global_load_dwordx4 v[134:137], v[130:131], off
.LBB0_513:
	v_add_u32_e32 v138, 56, v216
	v_mad_i64_i32 v[130:131], s[24:25], v138, s65, v[214:215]
	global_load_dwordx4 v[130:133], v[130:131], off nt
	v_ashrrev_i32_e32 v139, 31, v138
	v_lshlrev_b64 v[218:219], 12, v[138:139]
	v_mov_b32_e32 v120, 0
	s_and_b64 vcc, exec, s[4:5]
	v_mov_b32_e32 v138, 0
	v_mov_b32_e32 v139, 0
	v_mov_b32_e32 v140, 0
	v_mov_b32_e32 v141, 0
	s_cbranch_vccnz .LBB0_515
	v_lshl_add_u64 v[138:139], v[212:213], 0, v[218:219]
	global_load_dwordx4 v[138:141], v[138:139], off
; #define LAS __attribute__((address_space(3)))
; __device__ __forceinline__ float bf_lo(unsigned u) { return __uint_as_float(u << 16); }
; __device__ __forceinline__ float bf_hi(unsigned u) { return __uint_as_float(u & 0xffff0000u); }
;     __device__ __forceinline__ void operator()(const f32x4 (&acc)[2][2][4][2], const UnitD& u, int wr, int wc, int lane, LAS unsigned char* eb) const {
;     ...
;             for (int m = 0; m < 4; ++m) {
; #pragma unroll
;                 for (int bj = 0; bj < 2; ++bj) { const f32x4 a0 = acc[ai][bj][m][0], a1 = acc[ai][bj][m][1];
;                     u32x4 w; w.x = cvtpk(a0[0], a0[1]); w.y = cvtpk(a0[2], a0[3]); w.z = cvtpk(a1[0], a1[1]); w.w = cvtpk(a1[2], a1[3]);
;                     *(LAS u32x4*)(eb + epi_wr_off(fr, 4 * bj + fq)) = w; }
; #pragma unroll
;                 for (int hf = 0; hf < 2; ++hf) avs[m][hf] = *(const LAS u32x4*)(eb + (8 * hf + rr) * 128 + cl * 16);
;                 __builtin_amdgcn_sched_barrier(0);
;             }
; #pragma unroll
;             for (int m = 0; m < 4; ++m) {
; #pragma unroll
;                 for (int hf = 0; hf < 2; ++hf) { const int r = 8 * hf + rr, c = cl ^ (r & 7); const size_t row = (size_t)(u.pm * BM + ai * HALF + wr * 64 + m * 16 + r);
;                     const u32x4 av = avs[m][hf];
;                     const u32x4 g4 = gw[m][hf], o4 = ow[m][hf];
;                     u32x4 w;
;                     w.x = cvtpk(bf_lo(o4.x) + bf_lo(g4.x) * bf_lo(av.x), bf_hi(o4.x) + bf_hi(g4.x) * bf_hi(av.x));
;                     w.y = cvtpk(bf_lo(o4.y) + bf_lo(g4.y) * bf_lo(av.y), bf_hi(o4.y) + bf_hi(g4.y) * bf_hi(av.y));
;                     w.z = cvtpk(bf_lo(o4.z) + bf_lo(g4.z) * bf_lo(av.z), bf_hi(o4.z) + bf_hi(g4.z) * bf_hi(av.z));
;                     w.w = cvtpk(bf_lo(o4.w) + bf_lo(g4.w) * bf_lo(av.w), bf_hi(o4.w) + bf_hi(g4.w) * bf_hi(av.w));
;                     *(u32x4*)(O + row * DM + colw + 8 * c) = w; }
.LBB0_515:
	v_lshrrev_b32_e32 v196, 4, v121
	v_lshlrev_b32_e32 v197, 7, v121
	v_cvt_pk_bf16_f32 v108, v108, v109
	v_cvt_pk_bf16_f32 v109, v110, v111
	v_cvt_pk_bf16_f32 v110, v104, v105
	v_add_u32_e32 v104, 4, v196
	v_and_b32_e32 v197, 0x780, v197
	v_cvt_pk_bf16_f32 v126, v126, v127
	v_cvt_pk_bf16_f32 v127, v128, v129
	v_cvt_pk_bf16_f32 v128, v122, v123
	v_bitop3_b32 v122, v196, v121, 7 bitop3:0x78
	v_bitop3_b32 v104, v104, v121, 7 bitop3:0x78
	v_add_u32_e32 v197, s45, v197
	v_lshlrev_b32_e32 v199, 4, v121
	v_lshlrev_b32_e32 v122, 4, v122
	v_lshlrev_b32_e32 v104, 4, v104
	v_lshl_add_u32 v198, v237, 7, s45
	v_and_b32_e32 v199, 0x70, v199
	v_cvt_pk_bf16_f32 v129, v124, v125
	v_add_u32_e32 v217, v197, v122
	v_cvt_pk_bf16_f32 v111, v106, v107
	v_add_u32_e32 v237, v197, v104
	ds_write_b128 v217, v[126:129]
	ds_write_b128 v237, v[108:111]
	v_add_u32_e32 v238, v198, v199
	ds_read_b128 v[104:107], v238
	ds_read_b128 v[108:111], v238 offset:1024
	v_cvt_pk_bf16_f32 v116, v116, v117
	v_cvt_pk_bf16_f32 v117, v118, v119
	v_cvt_pk_bf16_f32 v118, v112, v113
	v_cvt_pk_bf16_f32 v119, v114, v115
	v_cvt_pk_bf16_f32 v92, v92, v93
	v_cvt_pk_bf16_f32 v93, v94, v95
	v_cvt_pk_bf16_f32 v94, v88, v89
	v_cvt_pk_bf16_f32 v95, v90, v91
	ds_write_b128 v217, v[116:119]
	ds_write_b128 v237, v[92:95]
	ds_read_b128 v[92:95], v238
	ds_read_b128 v[88:91], v238 offset:1024
	v_cvt_pk_bf16_f32 v100, v100, v101
	v_cvt_pk_bf16_f32 v101, v102, v103
	v_cvt_pk_bf16_f32 v102, v96, v97
	v_cvt_pk_bf16_f32 v103, v98, v99
	v_cvt_pk_bf16_f32 v76, v76, v77
	v_cvt_pk_bf16_f32 v77, v78, v79
	v_cvt_pk_bf16_f32 v78, v72, v73
	v_cvt_pk_bf16_f32 v79, v74, v75
	ds_write_b128 v217, v[100:103]
	ds_write_b128 v237, v[76:79]
	ds_read_b128 v[76:79], v238
	ds_read_b128 v[72:75], v238 offset:1024
	v_cvt_pk_bf16_f32 v84, v84, v85
	v_cvt_pk_bf16_f32 v85, v86, v87
	v_cvt_pk_bf16_f32 v86, v80, v81
	v_cvt_pk_bf16_f32 v87, v82, v83
	v_cvt_pk_bf16_f32 v68, v68, v69
	v_cvt_pk_bf16_f32 v69, v70, v71
	v_cvt_pk_bf16_f32 v70, v64, v65
	v_cvt_pk_bf16_f32 v71, v66, v67
	ds_write_b128 v217, v[84:87]
	ds_write_b128 v237, v[68:71]
	ds_read_b128 v[68:71], v238
	ds_read_b128 v[64:67], v238 offset:1024
	s_waitcnt vmcnt(0)
	v_lshlrev_b32_e32 v80, 16, v190
	v_and_b32_e32 v81, 0xffff0000, v190
	v_lshlrev_b32_e32 v82, 16, v186
	v_and_b32_e32 v83, 0xffff0000, v186
	s_waitcnt lgkmcnt(13)
	v_lshlrev_b32_e32 v84, 16, v104
	v_and_b32_e32 v85, 0xffff0000, v104
	v_pk_fma_f32 v[80:81], v[82:83], v[84:85], v[80:81]
	v_lshlrev_b32_e32 v82, 16, v191
	v_and_b32_e32 v83, 0xffff0000, v191
	v_lshlrev_b32_e32 v84, 16, v187
	v_and_b32_e32 v85, 0xffff0000, v187
	v_lshlrev_b32_e32 v86, 16, v105
	v_and_b32_e32 v87, 0xffff0000, v105
	v_pk_fma_f32 v[82:83], v[84:85], v[86:87], v[82:83]
	v_cvt_pk_bf16_f32 v80, v80, v81
	v_cvt_pk_bf16_f32 v81, v82, v83
	v_lshlrev_b32_e32 v82, 16, v192
	v_and_b32_e32 v83, 0xffff0000, v192
	v_lshlrev_b32_e32 v84, 16, v188
	v_and_b32_e32 v85, 0xffff0000, v188
	v_lshlrev_b32_e32 v86, 16, v106
	v_and_b32_e32 v87, 0xffff0000, v106
	v_pk_fma_f32 v[82:83], v[84:85], v[86:87], v[82:83]
	v_lshlrev_b32_e32 v84, 16, v193
	v_and_b32_e32 v85, 0xffff0000, v193
	v_lshlrev_b32_e32 v86, 16, v189
	v_and_b32_e32 v87, 0xffff0000, v189
	v_lshlrev_b32_e32 v96, 16, v107
	v_and_b32_e32 v97, 0xffff0000, v107
	v_pk_fma_f32 v[84:85], v[86:87], v[96:97], v[84:85]
	v_cvt_pk_bf16_f32 v82, v82, v83
	v_cvt_pk_bf16_f32 v83, v84, v85
	v_lshl_add_u64 v[84:85], s[10:11], 0, v[232:233]
	v_lshl_add_u64 v[84:85], v[84:85], 0, s[22:23]
	v_lshl_add_u64 v[84:85], v[84:85], 0, v[194:195]
	global_store_dwordx4 v[84:85], v[80:83], off
	s_waitcnt lgkmcnt(12)
	v_lshlrev_b32_e32 v84, 16, v108
	v_and_b32_e32 v85, 0xffff0000, v108
	v_lshlrev_b32_e32 v80, 16, v182
	v_and_b32_e32 v81, 0xffff0000, v182
	v_lshlrev_b32_e32 v82, 16, v178
	v_and_b32_e32 v83, 0xffff0000, v178
	v_pk_fma_f32 v[80:81], v[82:83], v[84:85], v[80:81]
	v_lshlrev_b32_e32 v82, 16, v183
	v_and_b32_e32 v83, 0xffff0000, v183
	v_lshlrev_b32_e32 v84, 16, v179
	v_and_b32_e32 v85, 0xffff0000, v179
	v_lshlrev_b32_e32 v86, 16, v109
	v_and_b32_e32 v87, 0xffff0000, v109
	v_pk_fma_f32 v[82:83], v[84:85], v[86:87], v[82:83]
	v_cvt_pk_bf16_f32 v80, v80, v81
	v_cvt_pk_bf16_f32 v81, v82, v83
	v_lshlrev_b32_e32 v82, 16, v184
	v_and_b32_e32 v83, 0xffff0000, v184
	v_lshlrev_b32_e32 v84, 16, v180
	v_and_b32_e32 v85, 0xffff0000, v180
	v_lshlrev_b32_e32 v86, 16, v110
	v_and_b32_e32 v87, 0xffff0000, v110
	v_pk_fma_f32 v[82:83], v[84:85], v[86:87], v[82:83]
	v_lshlrev_b32_e32 v84, 16, v185
	v_and_b32_e32 v85, 0xffff0000, v185
	v_lshlrev_b32_e32 v86, 16, v181
	v_and_b32_e32 v87, 0xffff0000, v181
	v_lshlrev_b32_e32 v96, 16, v111
	v_and_b32_e32 v97, 0xffff0000, v111
	v_pk_fma_f32 v[84:85], v[86:87], v[96:97], v[84:85]
	v_cvt_pk_bf16_f32 v82, v82, v83
	v_cvt_pk_bf16_f32 v83, v84, v85
	v_lshl_add_u64 v[84:85], s[10:11], 0, v[230:231]
	v_lshl_add_u64 v[84:85], v[84:85], 0, s[22:23]
	v_lshl_add_u64 v[84:85], v[84:85], 0, v[194:195]
	global_store_dwordx4 v[84:85], v[80:83], off
	s_waitcnt lgkmcnt(9)
; __device__ __forceinline__ float bf_lo(unsigned u) { return __uint_as_float(u << 16); }
; __device__ __forceinline__ float bf_hi(unsigned u) { return __uint_as_float(u & 0xffff0000u); }
;     __device__ __forceinline__ void operator()(const f32x4 (&acc)[2][2][4][2], const UnitD& u, int wr, int wc, int lane, LAS unsigned char* eb) const {
;     ...
;             for (int m = 0; m < 4; ++m) {
; #pragma unroll
;                 for (int hf = 0; hf < 2; ++hf) { const int r = 8 * hf + rr, c = cl ^ (r & 7); const size_t row = (size_t)(u.pm * BM + ai * HALF + wr * 64 + m * 16 + r);
;                     const u32x4 av = avs[m][hf];
;                     const u32x4 g4 = gw[m][hf], o4 = ow[m][hf];
;                     u32x4 w;
;                     w.x = cvtpk(bf_lo(o4.x) + bf_lo(g4.x) * bf_lo(av.x), bf_hi(o4.x) + bf_hi(g4.x) * bf_hi(av.x));
;                     w.y = cvtpk(bf_lo(o4.y) + bf_lo(g4.y) * bf_lo(av.y), bf_hi(o4.y) + bf_hi(g4.y) * bf_hi(av.y));
;                     w.z = cvtpk(bf_lo(o4.z) + bf_lo(g4.z) * bf_lo(av.z), bf_hi(o4.z) + bf_hi(g4.z) * bf_hi(av.z));
;                     w.w = cvtpk(bf_lo(o4.w) + bf_lo(g4.w) * bf_lo(av.w), bf_hi(o4.w) + bf_hi(g4.w) * bf_hi(av.w));
;                     *(u32x4*)(O + row * DM + colw + 8 * c) = w; }
	v_lshlrev_b32_e32 v84, 16, v92
	v_and_b32_e32 v85, 0xffff0000, v92
	v_lshlrev_b32_e32 v80, 16, v162
	v_and_b32_e32 v81, 0xffff0000, v162
	v_lshlrev_b32_e32 v82, 16, v174
	v_and_b32_e32 v83, 0xffff0000, v174
	v_pk_fma_f32 v[80:81], v[82:83], v[84:85], v[80:81]
	v_lshlrev_b32_e32 v82, 16, v163
	v_and_b32_e32 v83, 0xffff0000, v163
	v_lshlrev_b32_e32 v84, 16, v175
	v_and_b32_e32 v85, 0xffff0000, v175
	v_lshlrev_b32_e32 v86, 16, v93
	v_and_b32_e32 v87, 0xffff0000, v93
	v_pk_fma_f32 v[82:83], v[84:85], v[86:87], v[82:83]
	v_cvt_pk_bf16_f32 v80, v80, v81
	v_cvt_pk_bf16_f32 v81, v82, v83
	v_lshlrev_b32_e32 v82, 16, v164
	v_and_b32_e32 v83, 0xffff0000, v164
	v_lshlrev_b32_e32 v84, 16, v176
	v_and_b32_e32 v85, 0xffff0000, v176
	v_lshlrev_b32_e32 v86, 16, v94
	v_and_b32_e32 v87, 0xffff0000, v94
	v_pk_fma_f32 v[82:83], v[84:85], v[86:87], v[82:83]
	v_lshlrev_b32_e32 v84, 16, v165
	v_and_b32_e32 v85, 0xffff0000, v165
	v_lshlrev_b32_e32 v86, 16, v177
	v_and_b32_e32 v87, 0xffff0000, v177
	v_lshlrev_b32_e32 v92, 16, v95
	v_and_b32_e32 v93, 0xffff0000, v95
	v_pk_fma_f32 v[84:85], v[86:87], v[92:93], v[84:85]
	v_cvt_pk_bf16_f32 v82, v82, v83
	v_cvt_pk_bf16_f32 v83, v84, v85
	v_lshl_add_u64 v[84:85], s[10:11], 0, v[228:229]
	v_lshl_add_u64 v[84:85], v[84:85], 0, s[22:23]
	v_lshl_add_u64 v[84:85], v[84:85], 0, v[194:195]
	global_store_dwordx4 v[84:85], v[80:83], off
	s_waitcnt lgkmcnt(8)
	v_lshlrev_b32_e32 v84, 16, v88
	v_and_b32_e32 v85, 0xffff0000, v88
	v_lshlrev_b32_e32 v80, 16, v170
	v_and_b32_e32 v81, 0xffff0000, v170
	v_lshlrev_b32_e32 v82, 16, v166
	v_and_b32_e32 v83, 0xffff0000, v166
	v_pk_fma_f32 v[80:81], v[82:83], v[84:85], v[80:81]
	v_lshlrev_b32_e32 v82, 16, v171
	v_and_b32_e32 v83, 0xffff0000, v171
	v_lshlrev_b32_e32 v84, 16, v167
	v_and_b32_e32 v85, 0xffff0000, v167
	v_lshlrev_b32_e32 v86, 16, v89
	v_and_b32_e32 v87, 0xffff0000, v89
	v_pk_fma_f32 v[82:83], v[84:85], v[86:87], v[82:83]
	v_cvt_pk_bf16_f32 v80, v80, v81
	v_cvt_pk_bf16_f32 v81, v82, v83
	v_lshlrev_b32_e32 v82, 16, v172
	v_and_b32_e32 v83, 0xffff0000, v172
	v_lshlrev_b32_e32 v84, 16, v168
	v_and_b32_e32 v85, 0xffff0000, v168
	v_lshlrev_b32_e32 v86, 16, v90
	v_and_b32_e32 v87, 0xffff0000, v90
	v_pk_fma_f32 v[82:83], v[84:85], v[86:87], v[82:83]
	v_lshlrev_b32_e32 v84, 16, v173
	v_and_b32_e32 v85, 0xffff0000, v173
	v_lshlrev_b32_e32 v86, 16, v169
	v_and_b32_e32 v87, 0xffff0000, v169
	v_lshlrev_b32_e32 v88, 16, v91
	v_and_b32_e32 v89, 0xffff0000, v91
	v_pk_fma_f32 v[84:85], v[86:87], v[88:89], v[84:85]
	v_cvt_pk_bf16_f32 v82, v82, v83
	v_cvt_pk_bf16_f32 v83, v84, v85
	v_lshl_add_u64 v[84:85], s[10:11], 0, v[226:227]
	v_lshl_add_u64 v[84:85], v[84:85], 0, s[22:23]
	v_lshl_add_u64 v[84:85], v[84:85], 0, v[194:195]
	global_store_dwordx4 v[84:85], v[80:83], off
	s_waitcnt lgkmcnt(5)
	v_lshlrev_b32_e32 v84, 16, v76
	v_and_b32_e32 v85, 0xffff0000, v76
	v_lshlrev_b32_e32 v80, 16, v150
	v_and_b32_e32 v81, 0xffff0000, v150
	v_lshlrev_b32_e32 v82, 16, v158
	v_and_b32_e32 v83, 0xffff0000, v158
	v_pk_fma_f32 v[80:81], v[82:83], v[84:85], v[80:81]
	v_lshlrev_b32_e32 v82, 16, v159
	v_cvt_pk_bf16_f32 v76, v80, v81
	v_lshlrev_b32_e32 v80, 16, v151
	v_and_b32_e32 v81, 0xffff0000, v151
	v_and_b32_e32 v83, 0xffff0000, v159
	v_lshlrev_b32_e32 v84, 16, v77
	v_and_b32_e32 v85, 0xffff0000, v77
	v_pk_fma_f32 v[80:81], v[82:83], v[84:85], v[80:81]
	v_lshlrev_b32_e32 v82, 16, v160
	v_cvt_pk_bf16_f32 v77, v80, v81
	v_lshlrev_b32_e32 v80, 16, v152
	v_and_b32_e32 v81, 0xffff0000, v152
	v_and_b32_e32 v83, 0xffff0000, v160
	v_lshlrev_b32_e32 v84, 16, v78
	v_and_b32_e32 v85, 0xffff0000, v78
	v_pk_fma_f32 v[80:81], v[82:83], v[84:85], v[80:81]
	v_lshlrev_b32_e32 v82, 16, v161
	v_cvt_pk_bf16_f32 v78, v80, v81
	v_lshlrev_b32_e32 v80, 16, v153
	v_and_b32_e32 v81, 0xffff0000, v153
	v_and_b32_e32 v83, 0xffff0000, v161
	v_lshlrev_b32_e32 v84, 16, v79
	v_and_b32_e32 v85, 0xffff0000, v79
	v_pk_fma_f32 v[80:81], v[82:83], v[84:85], v[80:81]
	s_and_b64 vcc, exec, s[4:5]
	v_cvt_pk_bf16_f32 v79, v80, v81
	v_lshl_add_u64 v[80:81], s[10:11], 0, v[224:225]
	v_lshl_add_u64 v[80:81], v[80:81], 0, s[22:23]
	v_lshl_add_u64 v[80:81], v[80:81], 0, v[194:195]
	global_store_dwordx4 v[80:81], v[76:79], off
	s_waitcnt lgkmcnt(4)
	v_lshlrev_b32_e32 v80, 16, v72
	v_and_b32_e32 v81, 0xffff0000, v72
	v_lshlrev_b32_e32 v76, 16, v154
	v_and_b32_e32 v77, 0xffff0000, v154
	v_lshlrev_b32_e32 v78, 16, v146
	v_and_b32_e32 v79, 0xffff0000, v146
	v_pk_fma_f32 v[76:77], v[78:79], v[80:81], v[76:77]
	v_lshlrev_b32_e32 v78, 16, v147
	v_cvt_pk_bf16_f32 v72, v76, v77
	v_lshlrev_b32_e32 v76, 16, v155
	v_and_b32_e32 v77, 0xffff0000, v155
	v_and_b32_e32 v79, 0xffff0000, v147
	v_lshlrev_b32_e32 v80, 16, v73
	v_and_b32_e32 v81, 0xffff0000, v73
	v_pk_fma_f32 v[76:77], v[78:79], v[80:81], v[76:77]
	v_lshlrev_b32_e32 v78, 16, v148
	v_cvt_pk_bf16_f32 v73, v76, v77
	v_lshlrev_b32_e32 v76, 16, v156
	v_and_b32_e32 v77, 0xffff0000, v156
	v_and_b32_e32 v79, 0xffff0000, v148
	v_lshlrev_b32_e32 v80, 16, v74
	v_and_b32_e32 v81, 0xffff0000, v74
	v_pk_fma_f32 v[76:77], v[78:79], v[80:81], v[76:77]
	v_lshlrev_b32_e32 v78, 16, v149
	v_cvt_pk_bf16_f32 v74, v76, v77
	v_lshlrev_b32_e32 v76, 16, v157
	v_and_b32_e32 v77, 0xffff0000, v157
	v_and_b32_e32 v79, 0xffff0000, v149
	v_lshlrev_b32_e32 v80, 16, v75
	v_and_b32_e32 v81, 0xffff0000, v75
	v_pk_fma_f32 v[76:77], v[78:79], v[80:81], v[76:77]
	v_mov_b32_e32 v121, 0
	v_cvt_pk_bf16_f32 v75, v76, v77
	v_lshl_add_u64 v[76:77], s[10:11], 0, v[222:223]
	v_lshl_add_u64 v[76:77], v[76:77], 0, s[22:23]
	v_lshl_add_u64 v[76:77], v[76:77], 0, v[194:195]
	global_store_dwordx4 v[76:77], v[72:75], off
	s_waitcnt lgkmcnt(1)
; __device__ __forceinline__ float bf_lo(unsigned u) { return __uint_as_float(u << 16); }
; __device__ __forceinline__ float bf_hi(unsigned u) { return __uint_as_float(u & 0xffff0000u); }
;     __device__ __forceinline__ void operator()(const f32x4 (&acc)[2][2][4][2], const UnitD& u, int wr, int wc, int lane, LAS unsigned char* eb) const {
;     ...
;             for (int m = 0; m < 4; ++m)
; #pragma unroll
;                 for (int hf = 0; hf < 2; ++hf) { const int r = 8 * hf + rr, c = cl ^ (r & 7); const size_t row = (size_t)(u.pm * BM + ai * HALF + wr * 64 + m * 16 + r);
;                     gw[m][hf] = *(const u32x4*)(G + row * ldg + colw + 8 * c);
;                     ow[m][hf] = first ? (u32x4){0u, 0u, 0u, 0u} : *(const u32x4*)(O + row * DM + colw + 8 * c); }
;     ...
;             for (int m = 0; m < 4; ++m) {
; #pragma unroll
;                 for (int hf = 0; hf < 2; ++hf) { const int r = 8 * hf + rr, c = cl ^ (r & 7); const size_t row = (size_t)(u.pm * BM + ai * HALF + wr * 64 + m * 16 + r);
;                     const u32x4 av = avs[m][hf];
;                     const u32x4 g4 = gw[m][hf], o4 = ow[m][hf];
;                     u32x4 w;
;                     w.x = cvtpk(bf_lo(o4.x) + bf_lo(g4.x) * bf_lo(av.x), bf_hi(o4.x) + bf_hi(g4.x) * bf_hi(av.x));
;                     w.y = cvtpk(bf_lo(o4.y) + bf_lo(g4.y) * bf_lo(av.y), bf_hi(o4.y) + bf_hi(g4.y) * bf_hi(av.y));
;                     w.z = cvtpk(bf_lo(o4.z) + bf_lo(g4.z) * bf_lo(av.z), bf_hi(o4.z) + bf_hi(g4.z) * bf_hi(av.z));
;                     w.w = cvtpk(bf_lo(o4.w) + bf_lo(g4.w) * bf_lo(av.w), bf_hi(o4.w) + bf_hi(g4.w) * bf_hi(av.w));
;                     *(u32x4*)(O + row * DM + colw + 8 * c) = w; }
	v_lshlrev_b32_e32 v76, 16, v68
	v_and_b32_e32 v77, 0xffff0000, v68
	v_lshlrev_b32_e32 v72, 16, v134
	v_and_b32_e32 v73, 0xffff0000, v134
	v_lshlrev_b32_e32 v74, 16, v142
	v_and_b32_e32 v75, 0xffff0000, v142
	v_pk_fma_f32 v[72:73], v[74:75], v[76:77], v[72:73]
	v_lshlrev_b32_e32 v74, 16, v143
	v_cvt_pk_bf16_f32 v68, v72, v73
	v_lshlrev_b32_e32 v72, 16, v135
	v_and_b32_e32 v73, 0xffff0000, v135
	v_and_b32_e32 v75, 0xffff0000, v143
	v_lshlrev_b32_e32 v76, 16, v69
	v_and_b32_e32 v77, 0xffff0000, v69
	v_pk_fma_f32 v[72:73], v[74:75], v[76:77], v[72:73]
	v_lshlrev_b32_e32 v74, 16, v144
	v_cvt_pk_bf16_f32 v69, v72, v73
	v_lshlrev_b32_e32 v72, 16, v136
	v_and_b32_e32 v73, 0xffff0000, v136
	v_and_b32_e32 v75, 0xffff0000, v144
	v_lshlrev_b32_e32 v76, 16, v70
	v_and_b32_e32 v77, 0xffff0000, v70
	v_pk_fma_f32 v[72:73], v[74:75], v[76:77], v[72:73]
	v_lshlrev_b32_e32 v74, 16, v145
	v_cvt_pk_bf16_f32 v70, v72, v73
	v_lshlrev_b32_e32 v72, 16, v137
	v_and_b32_e32 v73, 0xffff0000, v137
	v_and_b32_e32 v75, 0xffff0000, v145
	v_lshlrev_b32_e32 v76, 16, v71
	v_and_b32_e32 v77, 0xffff0000, v71
	v_pk_fma_f32 v[72:73], v[74:75], v[76:77], v[72:73]
	v_mov_b32_e32 v122, 0
	v_cvt_pk_bf16_f32 v71, v72, v73
	v_lshl_add_u64 v[72:73], s[10:11], 0, v[220:221]
	v_lshl_add_u64 v[72:73], v[72:73], 0, s[22:23]
	v_lshl_add_u64 v[72:73], v[72:73], 0, v[194:195]
	global_store_dwordx4 v[72:73], v[68:71], off
	s_waitcnt lgkmcnt(0)
	v_lshlrev_b32_e32 v72, 16, v64
	v_and_b32_e32 v73, 0xffff0000, v64
	v_lshlrev_b32_e32 v68, 16, v138
	v_and_b32_e32 v69, 0xffff0000, v138
	v_lshlrev_b32_e32 v70, 16, v130
	v_and_b32_e32 v71, 0xffff0000, v130
	v_pk_fma_f32 v[68:69], v[70:71], v[72:73], v[68:69]
	v_lshlrev_b32_e32 v70, 16, v131
	v_cvt_pk_bf16_f32 v64, v68, v69
	v_lshlrev_b32_e32 v68, 16, v139
	v_and_b32_e32 v69, 0xffff0000, v139
	v_and_b32_e32 v71, 0xffff0000, v131
	v_lshlrev_b32_e32 v72, 16, v65
	v_and_b32_e32 v73, 0xffff0000, v65
	v_pk_fma_f32 v[68:69], v[70:71], v[72:73], v[68:69]
	v_lshlrev_b32_e32 v70, 16, v132
	v_cvt_pk_bf16_f32 v65, v68, v69
	v_lshlrev_b32_e32 v68, 16, v140
	v_and_b32_e32 v69, 0xffff0000, v140
	v_and_b32_e32 v71, 0xffff0000, v132
	v_lshlrev_b32_e32 v72, 16, v66
	v_and_b32_e32 v73, 0xffff0000, v66
	v_pk_fma_f32 v[68:69], v[70:71], v[72:73], v[68:69]
	v_lshlrev_b32_e32 v70, 16, v133
	v_cvt_pk_bf16_f32 v66, v68, v69
	v_lshlrev_b32_e32 v68, 16, v141
	v_and_b32_e32 v69, 0xffff0000, v141
	v_and_b32_e32 v71, 0xffff0000, v133
	v_lshlrev_b32_e32 v72, 16, v67
	v_and_b32_e32 v73, 0xffff0000, v67
	v_pk_fma_f32 v[68:69], v[70:71], v[72:73], v[68:69]
	v_mov_b32_e32 v123, 0
	v_cvt_pk_bf16_f32 v67, v68, v69
	v_lshl_add_u64 v[68:69], s[10:11], 0, v[218:219]
	v_lshl_add_u64 v[68:69], v[68:69], 0, s[22:23]
	v_lshl_add_u64 v[68:69], v[68:69], 0, v[194:195]
	global_store_dwordx4 v[68:69], v[64:67], off
	s_nop 1
	v_add_u32_e32 v64, 0x80, v216
	v_mad_i64_i32 v[66:67], s[24:25], v64, s65, v[214:215]
	global_load_dwordx4 v[124:127], v[66:67], off nt
	v_ashrrev_i32_e32 v65, 31, v64
	v_lshlrev_b64 v[142:143], 12, v[64:65]
	s_cbranch_vccnz .LBB0_517
	v_lshl_add_u64 v[64:65], v[212:213], 0, v[142:143]
	global_load_dwordx4 v[120:123], v[64:65], off
.LBB0_517:
	v_add_u32_e32 v64, 0x88, v216
	v_mad_i64_i32 v[66:67], s[24:25], v64, s65, v[214:215]
	global_load_dwordx4 v[112:115], v[66:67], off nt
	v_ashrrev_i32_e32 v65, 31, v64
	v_mov_b32_e32 v100, 0
	s_and_b64 vcc, exec, s[4:5]
	v_lshlrev_b64 v[140:141], 12, v[64:65]
	v_mov_b32_e32 v116, 0
	v_mov_b32_e32 v117, 0
	v_mov_b32_e32 v118, 0
	v_mov_b32_e32 v119, 0
	v_mov_b32_e32 v225, v247
	v_mov_b32_e32 v227, v248
	v_mov_b32_e32 v229, v249
	v_mov_b32_e32 v226, v242
	v_mov_b32_e32 v228, v241
	v_mov_b32_e32 v230, v240
	s_cbranch_vccnz .LBB0_519
	v_lshl_add_u64 v[64:65], v[212:213], 0, v[140:141]
	global_load_dwordx4 v[116:119], v[64:65], off
.LBB0_519:
	v_add_u32_e32 v64, 0x90, v216
	v_mad_i64_i32 v[66:67], s[24:25], v64, s65, v[214:215]
	global_load_dwordx4 v[108:111], v[66:67], off nt
	v_ashrrev_i32_e32 v65, 31, v64
	s_and_b64 vcc, exec, s[4:5]
	v_lshlrev_b64 v[138:139], 12, v[64:65]
	v_mov_b32_e32 v101, 0
	v_mov_b32_e32 v102, 0
	v_mov_b32_e32 v103, 0
	s_cbranch_vccnz .LBB0_521
	v_lshl_add_u64 v[64:65], v[212:213], 0, v[138:139]
	global_load_dwordx4 v[100:103], v[64:65], off
.LBB0_521:
	v_add_u32_e32 v64, 0x98, v216
	v_mad_i64_i32 v[66:67], s[24:25], v64, s65, v[214:215]
	global_load_dwordx4 v[96:99], v[66:67], off nt
	v_ashrrev_i32_e32 v65, 31, v64
	v_mov_b32_e32 v84, 0
	s_and_b64 vcc, exec, s[4:5]
	v_lshlrev_b64 v[136:137], 12, v[64:65]
	v_mov_b32_e32 v104, 0
	v_mov_b32_e32 v105, 0
	v_mov_b32_e32 v106, 0
	v_mov_b32_e32 v107, 0
	s_cbranch_vccnz .LBB0_523
	v_lshl_add_u64 v[64:65], v[212:213], 0, v[136:137]
	global_load_dwordx4 v[104:107], v[64:65], off
.LBB0_523:
	v_add_u32_e32 v64, 0xa0, v216
	v_mad_i64_i32 v[66:67], s[24:25], v64, s65, v[214:215]
	global_load_dwordx4 v[92:95], v[66:67], off nt
	v_ashrrev_i32_e32 v65, 31, v64
	s_and_b64 vcc, exec, s[4:5]
	v_lshlrev_b64 v[134:135], 12, v[64:65]
	v_mov_b32_e32 v85, 0
	v_mov_b32_e32 v86, 0
	v_mov_b32_e32 v87, 0
	s_cbranch_vccnz .LBB0_525
	v_lshl_add_u64 v[64:65], v[212:213], 0, v[134:135]
	global_load_dwordx4 v[84:87], v[64:65], off
.LBB0_525:
	v_add_u32_e32 v64, 0xa8, v216
	v_mad_i64_i32 v[66:67], s[24:25], v64, s65, v[214:215]
	global_load_dwordx4 v[80:83], v[66:67], off nt
	v_ashrrev_i32_e32 v65, 31, v64
	v_mov_b32_e32 v72, 0
	s_and_b64 vcc, exec, s[4:5]
	v_lshlrev_b64 v[132:133], 12, v[64:65]
	v_mov_b32_e32 v88, 0
	v_mov_b32_e32 v89, 0
	v_mov_b32_e32 v90, 0
	v_mov_b32_e32 v91, 0
	s_cbranch_vccnz .LBB0_527
	v_lshl_add_u64 v[64:65], v[212:213], 0, v[132:133]
	global_load_dwordx4 v[88:91], v[64:65], off
.LBB0_527:
	v_add_u32_e32 v64, 0xb0, v216
	v_mad_i64_i32 v[66:67], s[24:25], v64, s65, v[214:215]
	global_load_dwordx4 v[76:79], v[66:67], off nt
	v_ashrrev_i32_e32 v65, 31, v64
	s_and_b64 vcc, exec, s[4:5]
	v_lshlrev_b64 v[130:131], 12, v[64:65]
	v_mov_b32_e32 v73, 0
	v_mov_b32_e32 v74, 0
	v_mov_b32_e32 v75, 0
	s_cbranch_vccnz .LBB0_529
	v_lshl_add_u64 v[64:65], v[212:213], 0, v[130:131]
	global_load_dwordx4 v[72:75], v[64:65], off
.LBB0_529:
	v_add_u32_e32 v68, 0xb8, v216
	v_mad_i64_i32 v[64:65], s[24:25], v68, s65, v[214:215]
	global_load_dwordx4 v[64:67], v[64:65], off nt
	v_ashrrev_i32_e32 v69, 31, v68
	v_lshlrev_b64 v[128:129], 12, v[68:69]
	v_mov_b32_e32 v68, 0
	s_and_b64 vcc, exec, s[4:5]
	v_mov_b32_e32 v69, 0
	v_mov_b32_e32 v70, 0
	v_mov_b32_e32 v71, 0
	s_cbranch_vccnz .LBB0_531
	v_lshl_add_u64 v[68:69], v[212:213], 0, v[128:129]
	global_load_dwordx4 v[68:71], v[68:69], off

; #define LAS __attribute__((address_space(3)))
;     __device__ __forceinline__ void operator()(const f32x4 (&acc)[2][2][4][2], const UnitD& u, int wr, int wc, int lane, LAS unsigned char* eb) const {
;     ...
;         const int fr = lane & 15, fq = lane >> 4, rr = lane >> 3, cl = lane & 7;
;         const int b = (u.pm * BM) / SEQ;
;         const int colw = u.pn * BM + wc * 64;
; #pragma unroll
;         for (int ai = 0; ai < 2; ++ai) {
;             f32x4 xr[4][2][2];
; #pragma unroll
;             for (int m = 0; m < 4; ++m)
; #pragma unroll
;                 for (int bj = 0; bj < 2; ++bj)
; #pragma unroll
;                     for (int hf = 0; hf < 2; ++hf) { const int r = 8 * hf + rr, c = cl ^ (r & 7);
;                         xr[m][bj][hf] = *(const f32x4*)(xres + (size_t)(u.pm * BM + ai * HALF + wr * 64 + m * 16 + r) * DM + colw + 32 * bj + 4 * c); }
; #pragma unroll
;             for (int m = 0; m < 4; ++m)
; #pragma unroll
;                 for (int bj = 0; bj < 2; ++bj) {
; #pragma unroll
;                     for (int n = 0; n < 2; ++n) *(LAS f32x4*)(eb + epi_wr_off(fr, 2 * fq + n)) = acc[ai][bj][m][n];
; #pragma unroll
;                     for (int hf = 0; hf < 2; ++hf) { const int r = 8 * hf + rr, c = cl ^ (r & 7); const int col = colw + 32 * bj + 4 * c;
;                         const f32x4 av = *(const LAS f32x4*)(eb + r * 128 + cl * 16);
;                         const f32x4 rgv = *(const f32x4*)(rg + (size_t)b * NMOD + col);
;                         *(f32x4*)(out + (size_t)(u.pm * BM + ai * HALF + wr * 64 + m * 16 + r) * DM + col) = xr[m][bj][hf] + rgv * av; }
.LBB0_603:
	s_ashr_i32 s13, s33, 31
	v_mov_b32_e32 v132, v164
	s_lshr_b32 s13, s13, 28
	s_add_i32 s13, s33, s13
	v_ashrrev_i32_e32 v167, 3, v132
	s_ashr_i32 s15, s13, 4
	s_lshl_b32 s13, s45, 8
	v_xor_b32_e32 v128, v167, v132
	s_or_b32 s20, s13, s43
	v_lshlrev_b32_e32 v128, 2, v128
	s_lshl_b32 s13, s33, 8
	s_ashr_i32 s21, s20, 31
	v_and_b32_e32 v129, 28, v128
	s_add_i32 s13, s13, s39
	v_or_b32_e32 v128, s20, v129
	s_lshl_b64 s[20:21], s[20:21], 2
	s_add_u32 s20, s8, s20
	v_add_u32_e32 v160, s13, v167
	s_mul_hi_i32 s22, s15, 0x6000
	s_mulk_i32 s15, 0x6000
	s_addc_u32 s21, s9, s21
	v_lshlrev_b32_e32 v194, 2, v129
	v_lshl_add_u64 v[162:163], s[20:21], 0, v[194:195]
	v_ashrrev_i32_e32 v161, 31, v160
	v_ashrrev_i32_e32 v129, 31, v128
	s_add_u32 s20, s37, s15
	v_lshlrev_b64 v[196:197], 13, v[160:161]
	s_addc_u32 s21, s38, s22
	v_lshlrev_b64 v[158:159], 2, v[128:129]
	v_lshl_add_u64 v[130:131], v[162:163], 0, v[196:197]
	v_lshl_add_u64 v[156:157], s[20:21], 0, v[158:159]
	global_load_dwordx4 v[170:173], v[130:131], off nt
	global_load_dwordx4 v[174:177], v[156:157], off
	global_load_dwordx2 v[232:233], v[156:157], off
	global_load_dword v231, v[156:157], off offset:8
	global_load_dword v237, v[156:157], off offset:12
	global_load_dwordx2 v[248:249], v[156:157], off offset:128
	global_load_dword v247, v[156:157], off offset:136
	global_load_dword v238, v[156:157], off offset:140
	v_lshlrev_b32_e32 v128, 7, v132
	v_and_b32_e32 v128, 0x780, v128
	v_add_u32_e32 v135, s42, v128
	v_lshlrev_b32_e32 v128, 4, v132
	v_and_b32_e32 v128, 0x70, v128
	v_add_u32_e32 v194, s42, v128
	v_add_u32_e32 v128, 8, v160
	v_ashrrev_i32_e32 v129, 31, v128
	v_lshlrev_b64 v[128:129], 13, v[128:129]
	v_lshl_add_u64 v[128:129], v[162:163], 0, v[128:129]
	global_load_dwordx4 v[178:181], v[130:131], off offset:128 nt
	global_load_dwordx4 v[182:185], v[128:129], off nt
	global_load_dwordx4 v[186:189], v[128:129], off offset:128 nt
	v_add_u32_e32 v128, 16, v160
	v_add_u32_e32 v130, 24, v160
	v_ashrrev_i32_e32 v129, 31, v128
	v_ashrrev_i32_e32 v131, 31, v130
	v_lshlrev_b64 v[128:129], 13, v[128:129]
	v_lshlrev_b64 v[130:131], 13, v[130:131]
	v_lshl_add_u64 v[128:129], v[162:163], 0, v[128:129]
	v_lshl_add_u64 v[130:131], v[162:163], 0, v[130:131]
	global_load_dwordx4 v[190:193], v[128:129], off nt
	global_load_dwordx4 v[200:203], v[128:129], off offset:128 nt
	global_load_dwordx4 v[204:207], v[130:131], off nt
	global_load_dwordx4 v[208:211], v[130:131], off offset:128 nt
	v_add_u32_e32 v128, 32, v160
	v_add_u32_e32 v130, 40, v160
	v_ashrrev_i32_e32 v129, 31, v128
	v_ashrrev_i32_e32 v131, 31, v130
	v_lshlrev_b64 v[128:129], 13, v[128:129]
	v_lshlrev_b64 v[130:131], 13, v[130:131]
	v_lshl_add_u64 v[128:129], v[162:163], 0, v[128:129]
	v_lshl_add_u64 v[130:131], v[162:163], 0, v[130:131]
	global_load_dwordx4 v[212:215], v[128:129], off nt
	global_load_dwordx4 v[140:143], v[128:129], off offset:128 nt
	global_load_dwordx4 v[216:219], v[130:131], off nt
	global_load_dwordx4 v[136:139], v[130:131], off offset:128 nt
	v_add_u32_e32 v130, 56, v160
	v_ashrrev_i32_e32 v131, 31, v130
	v_and_b32_e32 v134, 7, v132
	v_lshlrev_b64 v[130:131], 13, v[130:131]
	s_mov_b32 s15, 0xffffffe
	v_lshl_add_u64 v[198:199], v[162:163], 0, v[130:131]
	v_bitop3_b32 v130, v167, v134, s15 bitop3:0x6c
	v_and_b32_e32 v133, 0xffffffe, v167
	v_lshl_add_u32 v168, v130, 4, v135
	ds_write_b128 v168, v[124:127]
	v_bitop3_b32 v124, v133, v134, 1 bitop3:0x36
	v_lshl_add_u32 v169, v124, 4, v135
	v_lshl_add_u32 v161, v167, 7, v194
	ds_write_b128 v169, v[120:123]
	ds_read_b128 v[220:223], v161
	v_add_u32_e32 v128, 48, v160
	v_ashrrev_i32_e32 v129, 31, v128
	v_lshlrev_b64 v[128:129], 13, v[128:129]
	v_lshl_add_u64 v[128:129], v[162:163], 0, v[128:129]
	global_load_dwordx4 v[132:135], v[128:129], off nt
	global_load_dwordx4 v[124:127], v[128:129], off offset:128 nt
	s_nop 0
	global_load_dwordx4 v[128:131], v[198:199], off nt
	global_load_dwordx4 v[120:123], v[198:199], off offset:128 nt
	s_or_b32 s15, s13, 16
	s_andn2_b64 vcc, exec, s[2:3]
	s_mov_b64 s[2:3], -1
	s_waitcnt vmcnt(0) lgkmcnt(0)
	v_pk_fma_f32 v[170:171], v[220:221], v[174:175], v[170:171]
	v_lshl_add_u64 v[174:175], s[4:5], 0, v[196:197]
	v_pk_fma_f32 v[172:173], v[222:223], v[176:177], v[172:173]
	v_lshl_add_u64 v[176:177], v[174:175], 0, v[158:159]
	global_store_dwordx4 v[176:177], v[170:173], off nt
	s_nop 1
	v_mov_b32_e32 v172, v232
	v_mov_b32_e32 v173, v233
	v_mov_b32_e32 v174, v231
	v_mov_b32_e32 v175, v237
	s_nop 0
	v_add_u32_e32 v171, 8, v167
	v_lshl_add_u32 v170, v171, 7, v194
	ds_read_b128 v[220:223], v170
	v_add_u32_e32 v196, s13, v171
	v_ashrrev_i32_e32 v197, 31, v196
	v_lshlrev_b64 v[196:197], 13, v[196:197]
	v_lshl_add_u64 v[196:197], s[4:5], 0, v[196:197]
	v_lshl_add_u64 v[196:197], v[196:197], 0, v[158:159]
	s_waitcnt lgkmcnt(0)
	v_pk_fma_f32 v[174:175], v[222:223], v[174:175], v[184:185]
	v_pk_fma_f32 v[172:173], v[220:221], v[172:173], v[182:183]
	global_store_dwordx4 v[196:197], v[172:175], off nt
	s_nop 1
	v_mov_b32_e32 v172, v248
	v_mov_b32_e32 v173, v249
	v_mov_b32_e32 v174, v247
	v_mov_b32_e32 v175, v238
	ds_write_b128 v168, v[116:119]
	ds_write_b128 v169, v[112:115]
	ds_read_b128 v[112:115], v161
	ds_read_b128 v[116:119], v170
	s_waitcnt lgkmcnt(1)
	v_pk_fma_f32 v[114:115], v[114:115], v[174:175], v[180:181]
	v_pk_fma_f32 v[112:113], v[112:113], v[172:173], v[178:179]
	global_store_dwordx4 v[176:177], v[112:115], off offset:128 nt
	s_nop 1
	v_mov_b32_e32 v112, v248
	v_mov_b32_e32 v113, v249
	v_mov_b32_e32 v114, v247
	v_mov_b32_e32 v115, v238
	s_waitcnt lgkmcnt(0)
; #define LAS __attribute__((address_space(3)))
;     __device__ __forceinline__ void operator()(const f32x4 (&acc)[2][2][4][2], const UnitD& u, int wr, int wc, int lane, LAS unsigned char* eb) const {
;     ...
;             for (int m = 0; m < 4; ++m)
; #pragma unroll
;                 for (int bj = 0; bj < 2; ++bj) {
; #pragma unroll
;                     for (int n = 0; n < 2; ++n) *(LAS f32x4*)(eb + epi_wr_off(fr, 2 * fq + n)) = acc[ai][bj][m][n];
; #pragma unroll
;                     for (int hf = 0; hf < 2; ++hf) { const int r = 8 * hf + rr, c = cl ^ (r & 7); const int col = colw + 32 * bj + 4 * c;
;                         const f32x4 av = *(const LAS f32x4*)(eb + r * 128 + cl * 16);
;                         const f32x4 rgv = *(const f32x4*)(rg + (size_t)b * NMOD + col);
;                         *(f32x4*)(out + (size_t)(u.pm * BM + ai * HALF + wr * 64 + m * 16 + r) * DM + col) = xr[m][bj][hf] + rgv * av; }
	v_pk_fma_f32 v[114:115], v[118:119], v[114:115], v[188:189]
	v_pk_fma_f32 v[112:113], v[116:117], v[112:113], v[186:187]
	global_store_dwordx4 v[196:197], v[112:115], off offset:128 nt
	s_nop 1
	v_mov_b32_e32 v112, v232
	v_mov_b32_e32 v113, v233
	v_mov_b32_e32 v114, v231
	v_mov_b32_e32 v115, v237
	ds_write_b128 v168, v[108:111]
	ds_write_b128 v169, v[104:107]
	ds_read_b128 v[104:107], v161
	v_add_u32_e32 v108, s15, v167
	v_ashrrev_i32_e32 v109, 31, v108
	v_lshlrev_b64 v[108:109], 13, v[108:109]
	v_lshl_add_u64 v[108:109], s[4:5], 0, v[108:109]
	v_lshl_add_u64 v[116:117], v[108:109], 0, v[158:159]
	ds_read_b128 v[108:111], v170
	s_waitcnt lgkmcnt(1)
	v_pk_fma_f32 v[106:107], v[106:107], v[114:115], v[192:193]
	v_pk_fma_f32 v[104:105], v[104:105], v[112:113], v[190:191]
	global_store_dwordx4 v[116:117], v[104:107], off nt
	s_nop 1
	v_mov_b32_e32 v104, v232
	v_mov_b32_e32 v105, v233
	v_mov_b32_e32 v106, v231
	v_mov_b32_e32 v107, v237
	v_add_u32_e32 v112, s15, v171
	v_ashrrev_i32_e32 v113, 31, v112
	v_lshlrev_b64 v[112:113], 13, v[112:113]
	v_lshl_add_u64 v[112:113], s[4:5], 0, v[112:113]
	v_lshl_add_u64 v[112:113], v[112:113], 0, v[158:159]
	s_or_b32 s15, s13, 32
	s_waitcnt lgkmcnt(0)
	v_pk_fma_f32 v[106:107], v[110:111], v[106:107], v[206:207]
	v_pk_fma_f32 v[104:105], v[108:109], v[104:105], v[204:205]
	global_store_dwordx4 v[112:113], v[104:107], off nt
	s_nop 1
	v_mov_b32_e32 v104, v248
	v_mov_b32_e32 v105, v249
	v_mov_b32_e32 v106, v247
	v_mov_b32_e32 v107, v238
	ds_write_b128 v168, v[100:103]
	ds_write_b128 v169, v[96:99]
	ds_read_b128 v[96:99], v161
	ds_read_b128 v[100:103], v170
	s_waitcnt lgkmcnt(1)
	v_pk_fma_f32 v[98:99], v[98:99], v[106:107], v[202:203]
	v_pk_fma_f32 v[96:97], v[96:97], v[104:105], v[200:201]
	global_store_dwordx4 v[116:117], v[96:99], off offset:128 nt
	s_nop 1
	v_mov_b32_e32 v96, v248
	v_mov_b32_e32 v97, v249
	v_mov_b32_e32 v98, v247
	v_mov_b32_e32 v99, v238
	s_waitcnt lgkmcnt(0)
	v_pk_fma_f32 v[98:99], v[102:103], v[98:99], v[210:211]
	v_pk_fma_f32 v[96:97], v[100:101], v[96:97], v[208:209]
	global_store_dwordx4 v[112:113], v[96:99], off offset:128 nt
	s_nop 1
	v_mov_b32_e32 v96, v232
	v_mov_b32_e32 v97, v233
	v_mov_b32_e32 v98, v231
	v_mov_b32_e32 v99, v237
	ds_write_b128 v168, v[92:95]
	ds_write_b128 v169, v[88:91]
	ds_read_b128 v[88:91], v161
	v_add_u32_e32 v100, s15, v167
	v_ashrrev_i32_e32 v101, 31, v100
	v_lshlrev_b64 v[92:93], 13, v[100:101]
	v_lshl_add_u64 v[92:93], s[4:5], 0, v[92:93]
	v_lshl_add_u64 v[100:101], v[92:93], 0, v[158:159]
	ds_read_b128 v[92:95], v170
	s_waitcnt lgkmcnt(1)
	v_pk_fma_f32 v[90:91], v[90:91], v[98:99], v[214:215]
	v_pk_fma_f32 v[88:89], v[88:89], v[96:97], v[212:213]
	global_store_dwordx4 v[100:101], v[88:91], off nt
	s_nop 1
	v_mov_b32_e32 v88, v232
	v_mov_b32_e32 v89, v233
	v_mov_b32_e32 v90, v231
	v_mov_b32_e32 v91, v237
	v_add_u32_e32 v96, s15, v171
	v_ashrrev_i32_e32 v97, 31, v96
	v_lshlrev_b64 v[96:97], 13, v[96:97]
	v_lshl_add_u64 v[96:97], s[4:5], 0, v[96:97]
	v_lshl_add_u64 v[96:97], v[96:97], 0, v[158:159]
	s_or_b32 s15, s13, 48
	s_waitcnt lgkmcnt(0)
	v_pk_fma_f32 v[90:91], v[94:95], v[90:91], v[218:219]
	v_pk_fma_f32 v[88:89], v[92:93], v[88:89], v[216:217]
	global_store_dwordx4 v[96:97], v[88:91], off nt
	s_nop 1
	v_mov_b32_e32 v88, v248
	v_mov_b32_e32 v89, v249
	v_mov_b32_e32 v90, v247
	v_mov_b32_e32 v91, v238
	ds_write_b128 v168, v[84:87]
	ds_write_b128 v169, v[80:83]
	ds_read_b128 v[80:83], v161
	ds_read_b128 v[84:87], v170
	s_waitcnt lgkmcnt(1)
	v_pk_fma_f32 v[82:83], v[82:83], v[90:91], v[142:143]
	v_pk_fma_f32 v[80:81], v[80:81], v[88:89], v[140:141]
	global_store_dwordx4 v[100:101], v[80:83], off offset:128 nt
	s_nop 1
	v_mov_b32_e32 v80, v248
	v_mov_b32_e32 v81, v249
	v_mov_b32_e32 v82, v247
	v_mov_b32_e32 v83, v238
	s_waitcnt lgkmcnt(0)
	v_pk_fma_f32 v[82:83], v[86:87], v[82:83], v[138:139]
	v_pk_fma_f32 v[80:81], v[84:85], v[80:81], v[136:137]
	global_store_dwordx4 v[96:97], v[80:83], off offset:128 nt
	s_nop 1
	v_mov_b32_e32 v80, v232
	v_mov_b32_e32 v81, v233
	v_mov_b32_e32 v82, v231
	v_mov_b32_e32 v83, v237
	ds_write_b128 v168, v[76:79]
	ds_write_b128 v169, v[72:75]
	ds_read_b128 v[72:75], v161
	v_add_u32_e32 v84, s15, v167
	v_ashrrev_i32_e32 v85, 31, v84
	v_lshlrev_b64 v[76:77], 13, v[84:85]
	v_lshl_add_u64 v[76:77], s[4:5], 0, v[76:77]
	v_lshl_add_u64 v[84:85], v[76:77], 0, v[158:159]
	ds_read_b128 v[76:79], v170
	v_add_u32_e32 v86, 0xb8, v160
	v_ashrrev_i32_e32 v87, 31, v86
	v_lshlrev_b64 v[86:87], 13, v[86:87]
	s_waitcnt lgkmcnt(1)
	v_pk_fma_f32 v[74:75], v[74:75], v[82:83], v[134:135]
	v_pk_fma_f32 v[72:73], v[72:73], v[80:81], v[132:133]
	global_store_dwordx4 v[84:85], v[72:75], off nt
	s_nop 1
	v_mov_b32_e32 v72, v232
	v_mov_b32_e32 v73, v233
	v_mov_b32_e32 v74, v231
	v_mov_b32_e32 v75, v237
	v_add_u32_e32 v80, s15, v171
	v_ashrrev_i32_e32 v81, 31, v80
	v_lshlrev_b64 v[80:81], 13, v[80:81]
	v_lshl_add_u64 v[80:81], s[4:5], 0, v[80:81]
	v_lshl_add_u64 v[80:81], v[80:81], 0, v[158:159]
	s_add_i32 s15, s13, 0x80
	s_waitcnt lgkmcnt(0)
	v_pk_fma_f32 v[74:75], v[78:79], v[74:75], v[130:131]
	v_pk_fma_f32 v[72:73], v[76:77], v[72:73], v[128:129]
	global_store_dwordx4 v[80:81], v[72:75], off nt
	s_nop 1
	v_mov_b32_e32 v72, v248
	v_mov_b32_e32 v73, v249
	v_mov_b32_e32 v74, v247
	v_mov_b32_e32 v75, v238
	ds_write_b128 v168, v[68:71]
	ds_write_b128 v169, v[64:67]
	ds_read_b128 v[64:67], v161
	ds_read_b128 v[68:71], v170
	v_lshl_add_u64 v[130:131], v[162:163], 0, v[86:87]
	s_waitcnt lgkmcnt(1)
; #define LAS __attribute__((address_space(3)))
;     __device__ __forceinline__ void operator()(const f32x4 (&acc)[2][2][4][2], const UnitD& u, int wr, int wc, int lane, LAS unsigned char* eb) const {
;     ...
;             f32x4 xr[4][2][2];
; #pragma unroll
;             for (int m = 0; m < 4; ++m)
; #pragma unroll
;                 for (int bj = 0; bj < 2; ++bj)
; #pragma unroll
;                     for (int hf = 0; hf < 2; ++hf) { const int r = 8 * hf + rr, c = cl ^ (r & 7);
;                         xr[m][bj][hf] = *(const f32x4*)(xres + (size_t)(u.pm * BM + ai * HALF + wr * 64 + m * 16 + r) * DM + colw + 32 * bj + 4 * c); }
; #pragma unroll
;             for (int m = 0; m < 4; ++m)
; #pragma unroll
;                 for (int bj = 0; bj < 2; ++bj) {
; #pragma unroll
;                     for (int n = 0; n < 2; ++n) *(LAS f32x4*)(eb + epi_wr_off(fr, 2 * fq + n)) = acc[ai][bj][m][n];
; #pragma unroll
;                     for (int hf = 0; hf < 2; ++hf) { const int r = 8 * hf + rr, c = cl ^ (r & 7); const int col = colw + 32 * bj + 4 * c;
;                         const f32x4 av = *(const LAS f32x4*)(eb + r * 128 + cl * 16);
;                         const f32x4 rgv = *(const f32x4*)(rg + (size_t)b * NMOD + col);
;                         *(f32x4*)(out + (size_t)(u.pm * BM + ai * HALF + wr * 64 + m * 16 + r) * DM + col) = xr[m][bj][hf] + rgv * av; }
	v_pk_fma_f32 v[66:67], v[66:67], v[74:75], v[126:127]
	v_pk_fma_f32 v[64:65], v[64:65], v[72:73], v[124:125]
	global_store_dwordx4 v[84:85], v[64:67], off offset:128 nt
	s_nop 1
	v_mov_b32_e32 v64, v248
	v_mov_b32_e32 v65, v249
	v_mov_b32_e32 v66, v247
	v_mov_b32_e32 v67, v238
	v_add_u32_e32 v72, 0x80, v160
	v_ashrrev_i32_e32 v73, 31, v72
	v_lshlrev_b64 v[72:73], 13, v[72:73]
	v_lshl_add_u64 v[82:83], v[162:163], 0, v[72:73]
	v_add_u32_e32 v84, 0xb0, v160
	v_ashrrev_i32_e32 v85, 31, v84
	v_lshlrev_b64 v[84:85], 13, v[84:85]
	v_lshl_add_u64 v[128:129], v[162:163], 0, v[84:85]
	s_waitcnt lgkmcnt(0)
	v_pk_fma_f32 v[66:67], v[70:71], v[66:67], v[122:123]
	v_pk_fma_f32 v[64:65], v[68:69], v[64:65], v[120:121]
	global_store_dwordx4 v[80:81], v[64:67], off offset:128 nt
	global_load_dwordx4 v[72:75], v[82:83], off nt
	s_nop 1
	v_mov_b32_e32 v76, v232
	v_mov_b32_e32 v77, v233
	v_mov_b32_e32 v78, v231
	v_mov_b32_e32 v79, v237
	v_add_u32_e32 v80, 0xa8, v160
	v_ashrrev_i32_e32 v81, 31, v80
	v_lshlrev_b64 v[80:81], 13, v[80:81]
	v_lshl_add_u64 v[120:121], v[162:163], 0, v[80:81]
	v_add_u32_e32 v80, s15, v167
	v_add_u32_e32 v64, 0x88, v160
	v_add_u32_e32 v66, 0x90, v160
	v_add_u32_e32 v68, 0x98, v160
	v_add_u32_e32 v70, 0xa0, v160
	v_ashrrev_i32_e32 v81, 31, v80
	v_ashrrev_i32_e32 v65, 31, v64
	v_ashrrev_i32_e32 v67, 31, v66
	v_ashrrev_i32_e32 v69, 31, v68
	v_ashrrev_i32_e32 v71, 31, v70
	v_lshlrev_b64 v[80:81], 13, v[80:81]
	v_lshlrev_b64 v[64:65], 13, v[64:65]
	v_lshlrev_b64 v[66:67], 13, v[66:67]
	v_lshlrev_b64 v[68:69], 13, v[68:69]
	v_lshlrev_b64 v[70:71], 13, v[70:71]
	v_lshl_add_u64 v[80:81], s[4:5], 0, v[80:81]
	ds_write_b128 v168, v[60:63]
	ds_write_b128 v169, v[56:59]
	v_lshl_add_u64 v[64:65], v[162:163], 0, v[64:65]
	v_lshl_add_u64 v[66:67], v[162:163], 0, v[66:67]
	v_lshl_add_u64 v[68:69], v[162:163], 0, v[68:69]
	v_lshl_add_u64 v[70:71], v[162:163], 0, v[70:71]
	v_lshl_add_u64 v[132:133], v[80:81], 0, v[158:159]
	global_load_dwordx4 v[80:83], v[82:83], off offset:128 nt
	s_nop 0
	global_load_dwordx4 v[84:87], v[64:65], off nt
	global_load_dwordx4 v[88:91], v[64:65], off offset:128 nt
	global_load_dwordx4 v[92:95], v[66:67], off nt
	global_load_dwordx4 v[96:99], v[66:67], off offset:128 nt
	global_load_dwordx4 v[100:103], v[68:69], off nt
	global_load_dwordx4 v[104:107], v[68:69], off offset:128 nt
	global_load_dwordx4 v[108:111], v[70:71], off nt
	global_load_dwordx4 v[112:115], v[70:71], off offset:128 nt
	global_load_dwordx4 v[116:119], v[120:121], off nt
	s_nop 0
	global_load_dwordx4 v[120:123], v[120:121], off offset:128 nt
	ds_read_b128 v[124:127], v161
	global_load_dwordx4 v[68:71], v[128:129], off nt
	global_load_dwordx4 v[60:63], v[128:129], off offset:128 nt
	global_load_dwordx4 v[64:67], v[130:131], off nt
	global_load_dwordx4 v[56:59], v[130:131], off offset:128 nt
	s_waitcnt vmcnt(15) lgkmcnt(0)
	v_pk_fma_f32 v[74:75], v[126:127], v[78:79], v[74:75]
	v_pk_fma_f32 v[72:73], v[124:125], v[76:77], v[72:73]
	global_store_dwordx4 v[132:133], v[72:75], off nt
	s_nop 1
	v_mov_b32_e32 v72, v232
	v_mov_b32_e32 v73, v233
	v_mov_b32_e32 v74, v231
	v_mov_b32_e32 v75, v237
	ds_read_b128 v[76:79], v170
	v_add_u32_e32 v124, s15, v171
	v_ashrrev_i32_e32 v125, 31, v124
	v_lshlrev_b64 v[124:125], 13, v[124:125]
	v_lshl_add_u64 v[124:125], s[4:5], 0, v[124:125]
	v_lshl_add_u64 v[124:125], v[124:125], 0, v[158:159]
	s_add_i32 s15, s13, 0x90
	s_waitcnt vmcnt(0) lgkmcnt(0)
	v_pk_fma_f32 v[74:75], v[78:79], v[74:75], v[86:87]
	v_pk_fma_f32 v[72:73], v[76:77], v[72:73], v[84:85]
	global_store_dwordx4 v[124:125], v[72:75], off nt
	s_nop 1
	v_mov_b32_e32 v72, v248
	v_mov_b32_e32 v73, v249
	v_mov_b32_e32 v74, v247
	v_mov_b32_e32 v75, v238
	ds_write_b128 v168, v[52:55]
	ds_write_b128 v169, v[48:51]
	ds_read_b128 v[48:51], v161
	ds_read_b128 v[52:55], v170
	s_waitcnt lgkmcnt(1)
	v_pk_fma_f32 v[50:51], v[50:51], v[74:75], v[82:83]
	v_pk_fma_f32 v[48:49], v[48:49], v[72:73], v[80:81]
	global_store_dwordx4 v[132:133], v[48:51], off offset:128 nt
	s_nop 1
	v_mov_b32_e32 v48, v248
	v_mov_b32_e32 v49, v249
	v_mov_b32_e32 v50, v247
	v_mov_b32_e32 v51, v238
	s_waitcnt lgkmcnt(0)
	v_pk_fma_f32 v[50:51], v[54:55], v[50:51], v[90:91]
	v_pk_fma_f32 v[48:49], v[52:53], v[48:49], v[88:89]
	global_store_dwordx4 v[124:125], v[48:51], off offset:128 nt
	s_nop 1
	v_mov_b32_e32 v48, v232
	v_mov_b32_e32 v49, v233
	v_mov_b32_e32 v50, v231
	v_mov_b32_e32 v51, v237
	ds_write_b128 v168, v[44:47]
	ds_write_b128 v169, v[40:43]
	ds_read_b128 v[40:43], v161
	v_add_u32_e32 v52, s15, v167
	v_ashrrev_i32_e32 v53, 31, v52
	v_lshlrev_b64 v[44:45], 13, v[52:53]
	v_lshl_add_u64 v[44:45], s[4:5], 0, v[44:45]
	v_lshl_add_u64 v[52:53], v[44:45], 0, v[158:159]
	ds_read_b128 v[44:47], v170
	s_waitcnt lgkmcnt(1)
; #define LAS __attribute__((address_space(3)))
; #define PG8_BAR __builtin_amdgcn_s_barrier()
;     __device__ __forceinline__ void operator()(const f32x4 (&acc)[2][2][4][2], const UnitD& u, int wr, int wc, int lane, LAS unsigned char* eb) const {
;     ...
;             for (int m = 0; m < 4; ++m)
; #pragma unroll
;                 for (int bj = 0; bj < 2; ++bj) {
; #pragma unroll
;                     for (int n = 0; n < 2; ++n) *(LAS f32x4*)(eb + epi_wr_off(fr, 2 * fq + n)) = acc[ai][bj][m][n];
; #pragma unroll
;                     for (int hf = 0; hf < 2; ++hf) { const int r = 8 * hf + rr, c = cl ^ (r & 7); const int col = colw + 32 * bj + 4 * c;
;                         const f32x4 av = *(const LAS f32x4*)(eb + r * 128 + cl * 16);
;                         const f32x4 rgv = *(const f32x4*)(rg + (size_t)b * NMOD + col);
;                         *(f32x4*)(out + (size_t)(u.pm * BM + ai * HALF + wr * 64 + m * 16 + r) * DM + col) = xr[m][bj][hf] + rgv * av; }
; template <class Epi, class Sched>
; __device__ __forceinline__ void gemm_stream(LAS unsigned char* lds, const int lda, const int ldb, const Sched& S, const Epi& E, const int wv) {
;     ...
;         if (wr == 0) PG8_BAR;
;         E(acc, cur, wr, wc, lane, lds + LDS_EPI + wid * 2048);
;         if (!has_next) break;
; #pragma unroll
;         for (int a = 0; a < 2; ++a)
; #pragma unroll
;             for (int b = 0; b < 2; ++b)
; #pragma unroll
;                 for (int m = 0; m < 4; ++m)
; #pragma unroll
;                     for (int n = 0; n < 2; ++n) acc[a][b][m][n] = (f32x4){0.f, 0.f, 0.f, 0.f};
;         cur = nxt; cA = nA; cB = nB; ++ui;
;         if (wr == 1) PG8_BAR;
	v_pk_fma_f32 v[42:43], v[42:43], v[50:51], v[94:95]
	v_pk_fma_f32 v[40:41], v[40:41], v[48:49], v[92:93]
	global_store_dwordx4 v[52:53], v[40:43], off nt
	s_nop 1
	v_mov_b32_e32 v40, v232
	v_mov_b32_e32 v41, v233
	v_mov_b32_e32 v42, v231
	v_mov_b32_e32 v43, v237
	v_add_u32_e32 v48, s15, v171
	v_ashrrev_i32_e32 v49, 31, v48
	v_lshlrev_b64 v[48:49], 13, v[48:49]
	v_lshl_add_u64 v[48:49], s[4:5], 0, v[48:49]
	v_lshl_add_u64 v[48:49], v[48:49], 0, v[158:159]
	s_add_i32 s15, s13, 0xa0
	s_addk_i32 s13, 0xb0
	s_waitcnt lgkmcnt(0)
	v_pk_fma_f32 v[42:43], v[46:47], v[42:43], v[102:103]
	v_pk_fma_f32 v[40:41], v[44:45], v[40:41], v[100:101]
	global_store_dwordx4 v[48:49], v[40:43], off nt
	s_nop 1
	v_mov_b32_e32 v40, v248
	v_mov_b32_e32 v41, v249
	v_mov_b32_e32 v42, v247
	v_mov_b32_e32 v43, v238
	ds_write_b128 v168, v[36:39]
	ds_write_b128 v169, v[32:35]
	ds_read_b128 v[32:35], v161
	ds_read_b128 v[36:39], v170
	s_waitcnt lgkmcnt(1)
	v_pk_fma_f32 v[34:35], v[34:35], v[42:43], v[98:99]
	v_pk_fma_f32 v[32:33], v[32:33], v[40:41], v[96:97]
	global_store_dwordx4 v[52:53], v[32:35], off offset:128 nt
	s_nop 1
	v_mov_b32_e32 v32, v248
	v_mov_b32_e32 v33, v249
	v_mov_b32_e32 v34, v247
	v_mov_b32_e32 v35, v238
	s_waitcnt lgkmcnt(0)
	v_pk_fma_f32 v[34:35], v[38:39], v[34:35], v[106:107]
	v_pk_fma_f32 v[32:33], v[36:37], v[32:33], v[104:105]
	global_store_dwordx4 v[48:49], v[32:35], off offset:128 nt
	s_nop 1
	v_mov_b32_e32 v32, v232
	v_mov_b32_e32 v33, v233
	v_mov_b32_e32 v34, v231
	v_mov_b32_e32 v35, v237
	ds_write_b128 v168, v[28:31]
	ds_write_b128 v169, v[24:27]
	ds_read_b128 v[24:27], v161
	v_add_u32_e32 v36, s15, v167
	v_ashrrev_i32_e32 v37, 31, v36
	v_lshlrev_b64 v[28:29], 13, v[36:37]
	v_lshl_add_u64 v[28:29], s[4:5], 0, v[28:29]
	v_lshl_add_u64 v[36:37], v[28:29], 0, v[158:159]
	ds_read_b128 v[28:31], v170
	s_waitcnt lgkmcnt(1)
	v_pk_fma_f32 v[26:27], v[26:27], v[34:35], v[110:111]
	v_pk_fma_f32 v[24:25], v[24:25], v[32:33], v[108:109]
	global_store_dwordx4 v[36:37], v[24:27], off nt
	s_nop 1
	v_mov_b32_e32 v24, v232
	v_mov_b32_e32 v25, v233
	v_mov_b32_e32 v26, v231
	v_mov_b32_e32 v27, v237
	v_add_u32_e32 v32, s15, v171
	v_ashrrev_i32_e32 v33, 31, v32
	v_lshlrev_b64 v[32:33], 13, v[32:33]
	v_lshl_add_u64 v[32:33], s[4:5], 0, v[32:33]
	v_lshl_add_u64 v[32:33], v[32:33], 0, v[158:159]
	s_waitcnt lgkmcnt(0)
	v_pk_fma_f32 v[26:27], v[30:31], v[26:27], v[118:119]
	v_pk_fma_f32 v[24:25], v[28:29], v[24:25], v[116:117]
	global_store_dwordx4 v[32:33], v[24:27], off nt
	s_nop 1
	v_mov_b32_e32 v24, v248
	v_mov_b32_e32 v25, v249
	v_mov_b32_e32 v26, v247
	v_mov_b32_e32 v27, v238
	ds_write_b128 v168, v[20:23]
	ds_write_b128 v169, v[16:19]
	ds_read_b128 v[16:19], v161
	ds_read_b128 v[20:23], v170
	s_waitcnt lgkmcnt(1)
	v_pk_fma_f32 v[18:19], v[18:19], v[26:27], v[114:115]
	v_pk_fma_f32 v[16:17], v[16:17], v[24:25], v[112:113]
	global_store_dwordx4 v[36:37], v[16:19], off offset:128 nt
	s_nop 1
	v_mov_b32_e32 v16, v248
	v_mov_b32_e32 v17, v249
	v_mov_b32_e32 v18, v247
	v_mov_b32_e32 v19, v238
	s_waitcnt lgkmcnt(0)
	v_pk_fma_f32 v[18:19], v[22:23], v[18:19], v[122:123]
	v_pk_fma_f32 v[16:17], v[20:21], v[16:17], v[120:121]
	global_store_dwordx4 v[32:33], v[16:19], off offset:128 nt
	s_nop 1
	v_mov_b32_e32 v16, v232
	v_mov_b32_e32 v17, v233
	v_mov_b32_e32 v18, v231
	v_mov_b32_e32 v19, v237
	ds_write_b128 v168, v[12:15]
	ds_write_b128 v169, v[8:11]
	ds_read_b128 v[8:11], v161
	v_add_u32_e32 v20, s13, v167
	v_ashrrev_i32_e32 v21, 31, v20
	v_lshlrev_b64 v[12:13], 13, v[20:21]
	v_lshl_add_u64 v[12:13], s[4:5], 0, v[12:13]
	v_lshl_add_u64 v[20:21], v[12:13], 0, v[158:159]
	ds_read_b128 v[12:15], v170
	s_waitcnt lgkmcnt(1)
	v_pk_fma_f32 v[10:11], v[10:11], v[18:19], v[70:71]
	v_pk_fma_f32 v[8:9], v[8:9], v[16:17], v[68:69]
	global_store_dwordx4 v[20:21], v[8:11], off nt
	s_nop 1
	v_mov_b32_e32 v8, v232
	v_mov_b32_e32 v9, v233
	v_mov_b32_e32 v10, v231
	v_mov_b32_e32 v11, v237
	v_add_u32_e32 v16, s13, v171
	v_ashrrev_i32_e32 v17, 31, v16
	v_lshlrev_b64 v[16:17], 13, v[16:17]
	v_lshl_add_u64 v[16:17], s[4:5], 0, v[16:17]
	v_lshl_add_u64 v[16:17], v[16:17], 0, v[158:159]
	s_waitcnt lgkmcnt(0)
	v_pk_fma_f32 v[10:11], v[14:15], v[10:11], v[66:67]
	v_pk_fma_f32 v[8:9], v[12:13], v[8:9], v[64:65]
	global_store_dwordx4 v[16:17], v[8:11], off nt
	s_nop 1
	v_mov_b32_e32 v8, v248
	v_mov_b32_e32 v9, v249
	v_mov_b32_e32 v10, v247
	v_mov_b32_e32 v11, v238
	ds_write_b128 v168, v[4:7]
	ds_write_b128 v169, v[0:3]
	ds_read_b128 v[0:3], v161
	ds_read_b128 v[4:7], v170
	s_waitcnt lgkmcnt(1)
	v_pk_fma_f32 v[2:3], v[2:3], v[10:11], v[62:63]
	v_pk_fma_f32 v[0:1], v[0:1], v[8:9], v[60:61]
	global_store_dwordx4 v[20:21], v[0:3], off offset:128 nt
	s_nop 1
	v_mov_b32_e32 v0, v248
	v_mov_b32_e32 v1, v249
	v_mov_b32_e32 v2, v247
	v_mov_b32_e32 v3, v238
	s_waitcnt lgkmcnt(0)
	v_pk_fma_f32 v[2:3], v[6:7], v[2:3], v[58:59]
	v_pk_fma_f32 v[0:1], v[4:5], v[0:1], v[56:57]
	global_store_dwordx4 v[16:17], v[0:3], off offset:128 nt
	s_cbranch_vccnz .LBB0_592
	s_andn2_b64 vcc, exec, s[10:11]
	s_cbranch_vccnz .LBB0_591
	s_barrier
	s_branch .LBB0_591
